# S5 output stage stagger: waves 4-7 delayed by s_sleep 20
# speedup vs baseline: 1.0019x; 1.0019x over previous
; #define LAS __attribute__((address_space(3)))
; #define S5_LAUNDER() int tid_ = tid0, lane_ = lane0; asm volatile("" : "+v"(tid_), "+v"(lane_)); const int tid = tid_, lane = lane_, fr = lane & 15, fq = lane >> 4; (void)tid; (void)fr; (void)fq
; __device__ __forceinline__ void s5_prompt_item_mfma(LAS unsigned char* lds, int tid0, int lane0, int wave, int n, int g, const bf16* USg, const bf16* FTg, const bf16* WTg, const bf16* GTg, ...
;     ...
;     S5_LAUNDER();
; #pragma unroll
;     for (int it = 0; it < 4; ++it) { const int q = tid + 512 * it; *(LAS v4u*)(lds + R2_OFF + q * 16) = ftq[it]; }
;     const f32x4 dk = *(const f32x4*)(dsk + 4 * fq);
;     __syncthreads();
;     bf16x8 hbv[4][4];
; #pragma unroll
;     for (int kk = 0; kk < 4; ++kk)
; #pragma unroll
;         for (int cb = 0; cb < 4; ++cb) hbv[kk][cb] = *(const LAS bf16x8*)(lds + HP_OFF + (16 * cb + fr) * 272 + 64 * kk + 16 * fq);
.LBB0_852:
	s_or_b64 exec, exec, s[54:55]
	v_mov_b32_e32 v201, v196
	v_mov_b32_e32 v2, v192
	s_lshl_b32 s10, s65, 6
	s_barrier
	s_add_u32 s10, s52, s10
	v_ashrrev_i32_e32 v202, 4, v201
	v_lshlrev_b32_e32 v194, 2, v202
	s_addc_u32 s11, s53, 0
	v_ashrrev_i32_e32 v195, 31, v194
	v_lshl_add_u64 v[20:21], v[194:195], 2, s[10:11]
	global_load_dwordx4 v[20:23], v[20:21], off
	s_add_i32 s10, 0, 0x10800
	v_and_b32_e32 v203, 15, v201
	v_lshl_add_u32 v2, v2, 4, s10
	s_waitcnt vmcnt(20)
	ds_write_b128 v2, v[24:27]
	s_waitcnt vmcnt(19)
	ds_write_b128 v2, v[28:31] offset:8192
	s_waitcnt vmcnt(18)
	ds_write_b128 v2, v[32:35] offset:16384
	s_waitcnt vmcnt(17)
	ds_write_b128 v2, v[36:39] offset:24576
	v_and_b32_e32 v2, -16, v201
	s_add_i32 s11, 0, 0x18c00
	v_mul_u32_u24_e32 v24, 0x110, v203
	v_add3_u32 v2, s11, v2, v24
	s_waitcnt lgkmcnt(0)
	s_barrier
	v_readfirstlane_b32 s99, v192
	s_nop 3
	s_lshr_b32 s99, s99, 6
	s_cmp_lt_u32 s99, 4
	s_cbranch_scc1 .Ls5_stag
	s_sleep 20
